# phase-3 weight conversion processes 4 consecutive k-tiles per iteration (was 2)
# baseline (speedup 1.0000x reference)
.LBB0_208:
	s_abs_i32 s0, s68
	v_cvt_f32_u32_e32 v0, s0
	s_sub_i32 s1, 0, s0
	v_writelane_b32 v254, s96, 8
	v_rcp_iflag_f32_e32 v0, v0
	s_nop 0
	v_writelane_b32 v254, s97, 9
	v_mul_f32_e32 v0, 0x4f7ffffe, v0
	v_cvt_u32_f32_e32 v0, v0
	s_nop 0
	v_readfirstlane_b32 s4, v0
	s_mul_i32 s1, s1, s4
	s_mul_hi_u32 s1, s4, s1
	s_add_i32 s4, s4, s1
	s_mul_hi_u32 s1, s4, 0x280
	s_mul_i32 s1, s1, s0
	s_sub_i32 s1, 0x280, s1
	s_sub_i32 s4, s1, s0
	s_cmp_ge_u32 s1, s0
	s_cselect_b32 s1, s4, s1
	s_sub_i32 s4, s1, s0
	s_cmp_ge_u32 s1, s0
	s_cselect_b32 s0, s4, s1
	s_sub_i32 s97, s2, s0
	s_sub_i32 s64, s68, s0
	s_lshl_b32 s84, s97, 2
	s_lshl_b32 s85, s64, 2
	s_cmp_lt_i32 s97, 0
	v_writelane_b32 v254, s0, 10
	s_cbranch_scc1 .LBB0_267
	s_cmpk_gt_u32 s84, 0xebf
	s_waitcnt vmcnt(0) lgkmcnt(0)
	s_barrier
	s_cbranch_scc1 .LBB0_267
	s_cmpk_lt_u32 s84, 0x580
	s_movk_i32 s0, 0x840
	s_cselect_b32 s1, 0x580, s0
	s_add_i32 s1, s1, s84
	s_cmpk_gt_u32 s1, 0xaff
	s_cbranch_scc0 .LBB0_217
	s_cmpk_gt_u32 s1, 0x107f
	s_cbranch_scc0 .LBB0_218
	s_cmpk_gt_u32 s1, 0x12ff
	s_cbranch_scc0 .LBB0_219
	s_cmpk_gt_u32 s1, 0x14ff
	s_cbranch_scc0 .LBB0_220
	s_cmpk_gt_u32 s1, 0x157f
	s_cbranch_scc0 .LBB0_221
	s_lshl_b32 s7, s1, 6
	s_cmpk_gt_u32 s1, 0x15ff
	s_cbranch_scc0 .LBB0_222
	s_lshl_b32 s0, s1, 2
	s_and_b32 s0, s0, 0x7fc0
	s_add_i32 s6, s0, 0xffffa800
	s_and_b32 s0, s7, 0x3c0
	s_mov_b64 s[8:9], 0
	s_mov_b64 s[4:5], s[50:51]
	s_branch .LBB0_223

.LBB0_239:
	s_ashr_i32 s1, s0, 31
	s_mul_hi_u32 s7, s16, s0
	s_mul_i32 s18, s16, s1
	s_add_i32 s7, s7, s18
	s_mul_i32 s17, s17, s0
	s_add_i32 s19, s7, s17
	s_mul_i32 s18, s16, s0
	s_lshl_b64 s[18:19], s[18:19], 2
	s_add_u32 s17, s4, s18
	s_addc_u32 s18, s5, s19
	s_ashr_i32 s7, s6, 31
	s_lshl_b64 s[4:5], s[6:7], 2
	s_add_u32 s4, s17, s4
	v_add_u32_e32 v14, 32, v194
	v_mov_b32_e32 v9, 0
	v_mul_u32_u24_e32 v2, s16, v194
	s_addc_u32 s5, s18, s5
	v_mul_hi_u32_u24_e32 v1, s16, v14
	v_mul_u32_u24_e32 v0, s16, v14
	v_lshlrev_b32_e32 v2, 2, v2
	v_mov_b32_e32 v3, v9
	v_lshl_add_u64 v[0:1], v[0:1], 2, s[4:5]
	v_lshlrev_b32_e32 v8, 4, v181
	v_lshl_add_u64 v[2:3], s[4:5], 0, v[2:3]
	v_lshl_add_u64 v[0:1], v[0:1], 0, v[8:9]
	v_lshl_add_u64 v[2:3], v[2:3], 0, v[8:9]
	s_lshl_b32 s86, s16, 8
	s_mov_b32 s87, 0
	v_lshl_add_u64 v[72:73], v[2:3], 0, s[86:87]
	v_lshl_add_u64 v[74:75], v[0:1], 0, s[86:87]
	global_load_dwordx4 v[4:7], v[0:1], off
	s_nop 0
	global_load_dwordx4 v[0:3], v[2:3], off
	global_load_dwordx4 v[28:31], v[72:73], off
	global_load_dwordx4 v[32:35], v[74:75], off
	v_lshl_add_u64 v[72:73], v[72:73], 0, s[86:87]
	v_lshl_add_u64 v[74:75], v[74:75], 0, s[86:87]
	global_load_dwordx4 v[36:39], v[72:73], off
	global_load_dwordx4 v[40:43], v[74:75], off
	v_lshl_add_u64 v[72:73], v[72:73], 0, s[86:87]
	v_lshl_add_u64 v[74:75], v[74:75], 0, s[86:87]
	global_load_dwordx4 v[44:47], v[72:73], off
	global_load_dwordx4 v[48:51], v[74:75], off
	s_add_u32 s6, s34, s8
	s_addc_u32 s7, s35, s9
	s_ashr_i32 s4, s20, 31
	s_mul_hi_u32 s5, s24, s20
	s_mul_i32 s4, s24, s4
	s_add_i32 s5, s5, s4
	s_mul_i32 s4, s24, s20
	s_lshl_b64 s[4:5], s[4:5], 1
	s_add_u32 s4, s6, s4
	s_addc_u32 s5, s7, s5
	s_lshl_b64 s[0:1], s[0:1], 1
	v_mul_u32_u24_e32 v11, 0x104, v194
	s_add_u32 s4, s4, s0
	v_add3_u32 v15, 0, v11, v8
	v_lshlrev_b32_e32 v8, 3, v146
	v_readlane_b32 s7, v254, 10
	s_addc_u32 s5, s5, s1
	v_and_b32_e32 v8, 56, v8
	s_lshl_b32 s0, s7, 1
	s_add_i32 s6, s2, s68
	v_mul_u32_u24_e32 v11, 0x104, v8
	v_lshlrev_b32_e32 v12, 2, v128
	s_sub_i32 s25, s68, s0
	s_sub_i32 s0, s6, s0
	v_lshlrev_b32_e32 v10, 2, v181
	v_add3_u32 v16, 0, v11, v12
	s_lshl_b32 s26, s0, 6
	s_lshl_b32 s0, s68, 6
	s_lshl_b32 s6, s7, 6
	s_mov_b32 s1, 0
	s_sub_i32 s27, s0, s6
	s_sub_i32 s33, 0, s7
	v_add_u32_e32 v17, 0x2080, v15
	v_add_u32_e32 v18, 0x2088, v15
	s_movk_i32 s65, 0x840
	s_mov_b32 s70, 0x1600000
	v_lshlrev_b32_e32 v10, 2, v10
	v_lshlrev_b32_e32 v12, 1, v8
	v_add_u32_e32 v19, 0x400, v16
	v_mov_b32_e32 v13, v9
	s_mov_b32 s71, s2
	s_lshl_b32 s25, s25, 2
	s_lshl_b32 s26, s26, 2
	s_lshl_b32 s27, s27, 2
	s_lshl_b32 s33, s33, 2
	s_lshl_b32 s71, s71, 2
	s_branch .LBB0_242
.LBB0_240:
	s_add_u32 s0, s34, s20
	s_addc_u32 s22, s35, s21
	s_ashr_i32 s7, s6, 31
	s_mul_hi_u32 s17, s18, s6
	s_mul_i32 s20, s18, s7
	s_add_i32 s17, s17, s20
	s_mul_i32 s19, s19, s6
	s_add_i32 s21, s17, s19
	s_mul_i32 s20, s18, s6
	s_ashr_i32 s17, s16, 31
	s_lshl_b64 s[20:21], s[20:21], 2
	s_add_u32 s19, s8, s20
	s_addc_u32 s20, s9, s21
	s_lshl_b64 s[8:9], s[16:17], 2
	s_add_u32 s8, s19, s8
	v_mul_u32_u24_e32 v0, s18, v194
	s_addc_u32 s9, s20, s9
	v_lshlrev_b32_e32 v8, 2, v0
	v_mul_hi_u32_u24_e32 v3, s18, v14
	v_mul_u32_u24_e32 v2, s18, v14
	v_lshl_add_u64 v[0:1], s[8:9], 0, v[8:9]
	v_mov_b32_e32 v11, v9
	v_lshl_add_u64 v[2:3], v[2:3], 2, s[8:9]
	v_lshl_add_u64 v[0:1], v[0:1], 0, v[10:11]
	v_lshl_add_u64 v[4:5], v[2:3], 0, v[10:11]
	s_lshl_b32 s86, s18, 8
	s_mov_b32 s87, 0
	v_lshl_add_u64 v[72:73], v[0:1], 0, s[86:87]
	v_lshl_add_u64 v[74:75], v[4:5], 0, s[86:87]
	global_load_dwordx4 v[0:3], v[0:1], off
	s_nop 0
	global_load_dwordx4 v[4:7], v[4:5], off
	global_load_dwordx4 v[28:31], v[72:73], off
	global_load_dwordx4 v[32:35], v[74:75], off
	v_lshl_add_u64 v[72:73], v[72:73], 0, s[86:87]
	v_lshl_add_u64 v[74:75], v[74:75], 0, s[86:87]
	global_load_dwordx4 v[36:39], v[72:73], off
	global_load_dwordx4 v[40:43], v[74:75], off
	v_lshl_add_u64 v[72:73], v[72:73], 0, s[86:87]
	v_lshl_add_u64 v[74:75], v[74:75], 0, s[86:87]
	global_load_dwordx4 v[44:47], v[72:73], off
	global_load_dwordx4 v[48:51], v[74:75], off
	s_ashr_i32 s8, s74, 31
	s_mul_hi_u32 s9, s72, s74
	s_mul_i32 s8, s72, s8
	s_add_i32 s9, s9, s8
	s_mul_i32 s8, s72, s74
	s_lshl_b64 s[8:9], s[8:9], 1
	s_add_u32 s0, s0, s8
	s_addc_u32 s8, s22, s9
	s_lshl_b64 s[6:7], s[6:7], 1
	s_add_u32 s6, s0, s6
	s_addc_u32 s7, s8, s7
.LBB0_241:
	s_waitcnt lgkmcnt(0)
	s_barrier
	ds_read2_b32 v[20:21], v16 offset1:65
	ds_read2_b32 v[22:23], v16 offset0:130 offset1:195
	ds_read2_b32 v[24:25], v19 offset0:4 offset1:69
	ds_read2_b32 v[26:27], v19 offset0:134 offset1:199
	s_add_i32 s71, s71, s85
	s_waitcnt lgkmcnt(3)
	v_cvt_pk_bf16_f32 v20, v20, v21
	s_waitcnt lgkmcnt(2)
	v_cvt_pk_bf16_f32 v21, v22, v23
	s_waitcnt lgkmcnt(1)
	v_cvt_pk_bf16_f32 v22, v24, v25
	v_mad_u64_u32 v[24:25], s[8:9], s24, v128, 0
	v_lshl_add_u64 v[24:25], v[24:25], 1, s[4:5]
	s_waitcnt lgkmcnt(0)
	v_cvt_pk_bf16_f32 v23, v26, v27
	v_lshl_add_u64 v[24:25], v[24:25], 0, v[12:13]
	global_store_dwordx4 v[24:25], v[20:23], off
	v_add_u32_e32 v52, 0x4100, v16
	v_add_u32_e32 v53, 0x4500, v16
	ds_read2_b32 v[56:57], v52 offset1:65
	ds_read2_b32 v[58:59], v52 offset0:130 offset1:195
	ds_read2_b32 v[60:61], v53 offset0:4 offset1:69
	ds_read2_b32 v[62:63], v53 offset0:134 offset1:199
	s_waitcnt lgkmcnt(3)
	v_cvt_pk_bf16_f32 v64, v56, v57
	s_waitcnt lgkmcnt(2)
	v_cvt_pk_bf16_f32 v65, v58, v59
	s_waitcnt lgkmcnt(1)
	v_cvt_pk_bf16_f32 v66, v60, v61
	s_waitcnt lgkmcnt(0)
	v_cvt_pk_bf16_f32 v67, v62, v63
	global_store_dwordx4 v[24:25], v[64:67], off offset:128
	s_nop 1
	v_add_u32_e32 v52, 0x8200, v16
	v_add_u32_e32 v53, 0x8600, v16
	ds_read2_b32 v[56:57], v52 offset1:65
	ds_read2_b32 v[58:59], v52 offset0:130 offset1:195
	ds_read2_b32 v[60:61], v53 offset0:4 offset1:69
	ds_read2_b32 v[62:63], v53 offset0:134 offset1:199
	s_waitcnt lgkmcnt(3)
	v_cvt_pk_bf16_f32 v64, v56, v57
	s_waitcnt lgkmcnt(2)
	v_cvt_pk_bf16_f32 v65, v58, v59
	s_waitcnt lgkmcnt(1)
	v_cvt_pk_bf16_f32 v66, v60, v61
	s_waitcnt lgkmcnt(0)
	v_cvt_pk_bf16_f32 v67, v62, v63
	global_store_dwordx4 v[24:25], v[64:67], off offset:256
	s_nop 1
	v_add_u32_e32 v52, 0xc300, v16
	v_add_u32_e32 v53, 0xc700, v16
	ds_read2_b32 v[56:57], v52 offset1:65
	ds_read2_b32 v[58:59], v52 offset0:130 offset1:195
	ds_read2_b32 v[60:61], v53 offset0:4 offset1:69
	ds_read2_b32 v[62:63], v53 offset0:134 offset1:199
	s_waitcnt lgkmcnt(3)
	v_cvt_pk_bf16_f32 v64, v56, v57
	s_waitcnt lgkmcnt(2)
	v_cvt_pk_bf16_f32 v65, v58, v59
	s_waitcnt lgkmcnt(1)
	v_cvt_pk_bf16_f32 v66, v60, v61
	s_waitcnt lgkmcnt(0)
	v_cvt_pk_bf16_f32 v67, v62, v63
	global_store_dwordx4 v[24:25], v[64:67], off offset:384
	s_nop 1
	s_waitcnt lgkmcnt(0)
	s_barrier
	s_add_i32 s26, s26, s27
	s_add_i32 s0, s33, s71
	s_cmpk_lt_i32 s0, 0xec0
	s_mov_b64 s[4:5], s[6:7]
	s_mov_b32 s24, s72
	s_cbranch_scc0 .LBB0_267
.LBB0_242:
	s_add_i32 s17, s25, s71
	s_mov_b64 s[6:7], 0
	s_cmpk_gt_i32 s17, 0xebf
	s_mov_b32 s72, 0
	s_waitcnt vmcnt(0)
	ds_write2_b32 v15, v0, v1 offset1:1
	ds_write2_b32 v17, v4, v5 offset1:1
	ds_write2_b32 v15, v2, v3 offset0:2 offset1:3
	ds_write2_b32 v18, v6, v7 offset1:1
	v_add_u32_e32 v52, 0x4100, v15
	v_add_u32_e32 v53, 0x6180, v15
	v_add_u32_e32 v54, 0x6188, v15
	ds_write2_b32 v52, v28, v29 offset1:1
	ds_write2_b32 v53, v32, v33 offset1:1
	ds_write2_b32 v52, v30, v31 offset0:2 offset1:3
	ds_write2_b32 v54, v34, v35 offset1:1
	v_add_u32_e32 v52, 0x8200, v15
	v_add_u32_e32 v53, 0xa280, v15
	v_add_u32_e32 v54, 0xa288, v15
	ds_write2_b32 v52, v36, v37 offset1:1
	ds_write2_b32 v53, v40, v41 offset1:1
	ds_write2_b32 v52, v38, v39 offset0:2 offset1:3
	ds_write2_b32 v54, v42, v43 offset1:1
	v_add_u32_e32 v52, 0xc300, v15
	v_add_u32_e32 v53, 0xe380, v15
	v_add_u32_e32 v54, 0xe388, v15
	ds_write2_b32 v52, v44, v45 offset1:1
	ds_write2_b32 v53, v48, v49 offset1:1
	ds_write2_b32 v52, v46, v47 offset0:2 offset1:3
	ds_write2_b32 v54, v50, v51 offset1:1
	s_cbranch_scc1 .LBB0_241
	s_cmpk_lt_i32 s17, 0x580
	s_cselect_b32 s73, 0x580, s65
	s_add_i32 s7, s25, s73
	s_add_i32 s7, s7, s71
	s_cmpk_gt_i32 s7, 0xaff
	s_mov_b64 s[22:23], -1
	s_cbranch_scc0 .LBB0_263
	s_cmpk_gt_u32 s7, 0x107f
	s_cbranch_scc0 .LBB0_260
	s_cmpk_gt_u32 s7, 0x12ff
	s_cbranch_scc0 .LBB0_251
	s_cmpk_gt_u32 s7, 0x14ff
	s_cbranch_scc0 .LBB0_252
	s_cmpk_gt_u32 s7, 0x157f
	s_cbranch_scc0 .LBB0_253
	s_lshl_b32 s0, s7, 6
	s_cmpk_gt_u32 s7, 0x15ff
	s_cbranch_scc0 .LBB0_265
	s_lshl_b32 s6, s7, 2
	s_and_b32 s6, s6, 0x7fffffc0
	s_add_i32 s16, s6, 0xffffa800
	s_and_b32 s6, s0, 0x3c0
	s_mov_b64 s[8:9], s[50:51]
	s_cbranch_execz .LBB0_266
	s_mov_b64 s[20:21], 0x2f00000
	s_movk_i32 s72, 0x400
	s_cbranch_execz .LBB0_254
	s_branch .LBB0_255
